# EpiUp H stores lane-transposed with ds_bpermute so each lane quad writes one contiguous 64B row segment (coalesced)
# speedup vs baseline: 1.0280x; 1.0105x over previous
; __device__ __forceinline__ unsigned pk2(float lo, float hi) { f32x2 v = {lo, hi}; bf16x2_t b = __builtin_convertvector(v, bf16x2_t); return __builtin_bit_cast(unsigned, b); }
;     __device__ __forceinline__ void operator()(const f32x4 (&acc)[2][2][4][2], const Unit& u, int wr, int wc, int fr, int fq) const {
; #pragma unroll
;         for (int ai = 0; ai < 2; ++ai)
; #pragma unroll
;             for (int m = 0; m < 4; ++m) {
;                 const size_t row = (size_t)u.pm * 256 + 128 * wr + 64 * ai + 16 * m + fr;
;                 const f32x4* sp = (const f32x4*)(ssq + row * 16);
;                 const f32x4 t = (sp[0] + sp[1]) + (sp[2] + sp[3]);
;                 const float r = __builtin_amdgcn_rsqf(((t[0] + t[1]) + (t[2] + t[3])) * (1.0f / DM) + EPS);
;                 const size_t off = (((size_t)u.pm * 64 + 4 * u.pn + (wc >> 1)) * 256 + (128 * wr + 64 * ai + 16 * m + fr)) * 64 + 32 * (wc & 1) + 8 * fq;
; #pragma unroll
;                 for (int bj = 0; bj < 2; ++bj) {
;                     f32x4 v0 = acc[ai][bj][m][0] * r, v1 = acc[ai][bj][m][1] * r;
; #pragma unroll
;                     for (int j = 0; j < 4; ++j) { v0[j] = fmaxf(v0[j], 0.f); v1[j] = fmaxf(v1[j], 0.f); }
;                     v0 = v0 * v0; v1 = v1 * v1;
;                     u32x4 w; w.x = pk2(v0[0], v0[1]); w.y = pk2(v0[2], v0[3]); w.z = pk2(v1[0], v1[1]); w.w = pk2(v1[2], v1[3]);
;                     *(u32x4*)(H + off + (size_t)bj * (2 * 256 * 64)) = w;
;                 }
.Lp4_rstd_cached:
	s_or_b64 s[6:7], s[6:7], s[86:87]
	s_lshl_b64 s[6:7], s[6:7], 15
	s_add_u32 s10, s46, s6
	s_addc_u32 s11, s47, s7
	s_mov_b64 s[14:15], 0x10000
	v_and_b32_e32 v208, 63, v0
	v_and_b32_e32 v209, 3, v208
	v_lshrrev_b32_e32 v210, 2, v208
	v_lshl_add_u32 v211, v209, 4, v210
	v_and_b32_e32 v212, 15, v208
	v_lshrrev_b32_e32 v213, 4, v208
	v_lshlrev_b32_e32 v211, 2, v211
	v_sub_u32_e32 v212, v210, v212
	v_sub_u32_e32 v213, v209, v213
	v_lshlrev_b32_e32 v212, 7, v212
	v_lshl_add_u32 v212, v213, 4, v212
	v_ashrrev_i32_e32 v213, 31, v212
	v_lshl_add_u64 v[214:215], v[134:135], 0, v[212:213]
	s_waitcnt lgkmcnt(0)
	v_pk_mul_f32 v[114:115], v[114:115], v[244:245] op_sel_hi:[1,0]
	v_pk_mul_f32 v[116:117], v[116:117], v[244:245] op_sel_hi:[1,0]
	v_pk_mul_f32 v[118:119], v[118:119], v[244:245] op_sel_hi:[1,0]
	v_pk_mul_f32 v[120:121], v[120:121], v[244:245] op_sel_hi:[1,0]
	v_pk_mul_f32 v[122:123], v[122:123], v[244:245] op_sel_hi:[1,0]
	v_pk_mul_f32 v[124:125], v[124:125], v[244:245] op_sel_hi:[1,0]
	v_pk_mul_f32 v[126:127], v[126:127], v[244:245] op_sel_hi:[1,0]
	v_pk_mul_f32 v[128:129], v[128:129], v[244:245] op_sel_hi:[1,0]
	v_lshl_add_u64 v[204:205], s[10:11], 0, v[144:145]
	v_max_f32_e32 v114, 0, v114
	v_max_f32_e32 v115, 0, v115
	v_max_f32_e32 v116, 0, v116
	v_max_f32_e32 v117, 0, v117
	v_max_f32_e32 v118, 0, v118
	v_max_f32_e32 v119, 0, v119
	v_max_f32_e32 v120, 0, v120
	v_max_f32_e32 v121, 0, v121
	v_max_f32_e32 v122, 0, v122
	v_max_f32_e32 v123, 0, v123
	v_max_f32_e32 v124, 0, v124
	v_max_f32_e32 v125, 0, v125
	v_max_f32_e32 v126, 0, v126
	v_max_f32_e32 v127, 0, v127
	v_max_f32_e32 v128, 0, v128
	v_max_f32_e32 v129, 0, v129
	v_lshl_add_u64 v[204:205], v[204:205], 0, s[62:63]
	v_pk_mul_f32 v[114:115], v[114:115], v[114:115]
	v_pk_mul_f32 v[116:117], v[116:117], v[116:117]
	v_pk_mul_f32 v[118:119], v[118:119], v[118:119]
	v_pk_mul_f32 v[120:121], v[120:121], v[120:121]
	v_pk_mul_f32 v[122:123], v[122:123], v[122:123]
	v_pk_mul_f32 v[124:125], v[124:125], v[124:125]
	v_pk_mul_f32 v[126:127], v[126:127], v[126:127]
	v_pk_mul_f32 v[128:129], v[128:129], v[128:129]
	v_lshl_add_u64 v[204:205], v[204:205], 0, v[214:215]
	v_cvt_pk_bf16_f32 v126, v126, v127
	v_cvt_pk_bf16_f32 v127, v128, v129
	v_cvt_pk_bf16_f32 v128, v122, v123
	v_cvt_pk_bf16_f32 v129, v124, v125
	v_lshl_add_u64 v[206:207], v[204:205], 0, s[14:15]
	ds_bpermute_b32 v126, v211, v126
	ds_bpermute_b32 v127, v211, v127
	ds_bpermute_b32 v128, v211, v128
	ds_bpermute_b32 v129, v211, v129
	v_cvt_pk_bf16_f32 v118, v118, v119
	v_cvt_pk_bf16_f32 v119, v120, v121
	v_cvt_pk_bf16_f32 v120, v114, v115
	v_cvt_pk_bf16_f32 v121, v116, v117
	ds_bpermute_b32 v118, v211, v118
	ds_bpermute_b32 v119, v211, v119
	ds_bpermute_b32 v120, v211, v120
	ds_bpermute_b32 v121, v211, v121
	v_pk_mul_f32 v[98:99], v[98:99], v[244:245] op_sel:[0,1]
	v_pk_mul_f32 v[100:101], v[100:101], v[244:245] op_sel:[0,1]
	v_pk_mul_f32 v[102:103], v[102:103], v[244:245] op_sel:[0,1]
	v_pk_mul_f32 v[104:105], v[104:105], v[244:245] op_sel:[0,1]
	v_pk_mul_f32 v[106:107], v[106:107], v[244:245] op_sel:[0,1]
	v_pk_mul_f32 v[108:109], v[108:109], v[244:245] op_sel:[0,1]
	v_pk_mul_f32 v[110:111], v[110:111], v[244:245] op_sel:[0,1]
	v_pk_mul_f32 v[112:113], v[112:113], v[244:245] op_sel:[0,1]
	v_lshl_add_u64 v[216:217], s[10:11], 0, v[146:147]
	v_max_f32_e32 v98, 0, v98
	v_max_f32_e32 v99, 0, v99
	v_max_f32_e32 v100, 0, v100
	v_max_f32_e32 v101, 0, v101
	v_max_f32_e32 v102, 0, v102
	v_max_f32_e32 v103, 0, v103
	v_max_f32_e32 v104, 0, v104
	v_max_f32_e32 v105, 0, v105
	v_max_f32_e32 v106, 0, v106
	v_max_f32_e32 v107, 0, v107
	v_max_f32_e32 v108, 0, v108
	v_max_f32_e32 v109, 0, v109
	v_max_f32_e32 v110, 0, v110
	v_max_f32_e32 v111, 0, v111
	v_max_f32_e32 v112, 0, v112
	v_max_f32_e32 v113, 0, v113
	v_lshl_add_u64 v[216:217], v[216:217], 0, s[62:63]
	v_pk_mul_f32 v[98:99], v[98:99], v[98:99]
	v_pk_mul_f32 v[100:101], v[100:101], v[100:101]
	v_pk_mul_f32 v[102:103], v[102:103], v[102:103]
	v_pk_mul_f32 v[104:105], v[104:105], v[104:105]
	v_pk_mul_f32 v[106:107], v[106:107], v[106:107]
	v_pk_mul_f32 v[108:109], v[108:109], v[108:109]
	v_pk_mul_f32 v[110:111], v[110:111], v[110:111]
	v_pk_mul_f32 v[112:113], v[112:113], v[112:113]
	v_lshl_add_u64 v[216:217], v[216:217], 0, v[214:215]
	v_cvt_pk_bf16_f32 v110, v110, v111
	v_cvt_pk_bf16_f32 v111, v112, v113
	v_cvt_pk_bf16_f32 v112, v106, v107
	v_cvt_pk_bf16_f32 v113, v108, v109
	v_lshl_add_u64 v[218:219], v[216:217], 0, s[14:15]
	ds_bpermute_b32 v110, v211, v110
	ds_bpermute_b32 v111, v211, v111
	ds_bpermute_b32 v112, v211, v112
	ds_bpermute_b32 v113, v211, v113
	v_cvt_pk_bf16_f32 v102, v102, v103
	v_cvt_pk_bf16_f32 v103, v104, v105
	v_cvt_pk_bf16_f32 v104, v98, v99
	v_cvt_pk_bf16_f32 v105, v100, v101
	ds_bpermute_b32 v102, v211, v102
	ds_bpermute_b32 v103, v211, v103
	ds_bpermute_b32 v104, v211, v104
	ds_bpermute_b32 v105, v211, v105
	s_waitcnt lgkmcnt(8)
; __device__ __forceinline__ unsigned pk2(float lo, float hi) { f32x2 v = {lo, hi}; bf16x2_t b = __builtin_convertvector(v, bf16x2_t); return __builtin_bit_cast(unsigned, b); }
;     __device__ __forceinline__ void operator()(const f32x4 (&acc)[2][2][4][2], const Unit& u, int wr, int wc, int fr, int fq) const {
; #pragma unroll
;         for (int ai = 0; ai < 2; ++ai)
; #pragma unroll
;             for (int m = 0; m < 4; ++m) {
;                 const size_t row = (size_t)u.pm * 256 + 128 * wr + 64 * ai + 16 * m + fr;
;                 const f32x4* sp = (const f32x4*)(ssq + row * 16);
;                 const f32x4 t = (sp[0] + sp[1]) + (sp[2] + sp[3]);
;                 const float r = __builtin_amdgcn_rsqf(((t[0] + t[1]) + (t[2] + t[3])) * (1.0f / DM) + EPS);
;                 const size_t off = (((size_t)u.pm * 64 + 4 * u.pn + (wc >> 1)) * 256 + (128 * wr + 64 * ai + 16 * m + fr)) * 64 + 32 * (wc & 1) + 8 * fq;
; #pragma unroll
;                 for (int bj = 0; bj < 2; ++bj) {
;                     f32x4 v0 = acc[ai][bj][m][0] * r, v1 = acc[ai][bj][m][1] * r;
; #pragma unroll
;                     for (int j = 0; j < 4; ++j) { v0[j] = fmaxf(v0[j], 0.f); v1[j] = fmaxf(v1[j], 0.f); }
;                     v0 = v0 * v0; v1 = v1 * v1;
;                     u32x4 w; w.x = pk2(v0[0], v0[1]); w.y = pk2(v0[2], v0[3]); w.z = pk2(v1[0], v1[1]); w.w = pk2(v1[2], v1[3]);
;                     *(u32x4*)(H + off + (size_t)bj * (2 * 256 * 64)) = w;
;                 }
	global_store_dwordx4 v[204:205], v[126:129], off
	global_store_dwordx4 v[206:207], v[118:121], off
	v_pk_mul_f32 v[82:83], v[82:83], v[246:247] op_sel_hi:[1,0]
	v_pk_mul_f32 v[84:85], v[84:85], v[246:247] op_sel_hi:[1,0]
	v_pk_mul_f32 v[86:87], v[86:87], v[246:247] op_sel_hi:[1,0]
	v_pk_mul_f32 v[88:89], v[88:89], v[246:247] op_sel_hi:[1,0]
	v_pk_mul_f32 v[90:91], v[90:91], v[246:247] op_sel_hi:[1,0]
	v_pk_mul_f32 v[92:93], v[92:93], v[246:247] op_sel_hi:[1,0]
	v_pk_mul_f32 v[94:95], v[94:95], v[246:247] op_sel_hi:[1,0]
	v_pk_mul_f32 v[96:97], v[96:97], v[246:247] op_sel_hi:[1,0]
	v_lshl_add_u64 v[204:205], s[10:11], 0, v[148:149]
	v_max_f32_e32 v82, 0, v82
	v_max_f32_e32 v83, 0, v83
	v_max_f32_e32 v84, 0, v84
	v_max_f32_e32 v85, 0, v85
	v_max_f32_e32 v86, 0, v86
	v_max_f32_e32 v87, 0, v87
	v_max_f32_e32 v88, 0, v88
	v_max_f32_e32 v89, 0, v89
	v_max_f32_e32 v90, 0, v90
	v_max_f32_e32 v91, 0, v91
	v_max_f32_e32 v92, 0, v92
	v_max_f32_e32 v93, 0, v93
	v_max_f32_e32 v94, 0, v94
	v_max_f32_e32 v95, 0, v95
	v_max_f32_e32 v96, 0, v96
	v_max_f32_e32 v97, 0, v97
	v_lshl_add_u64 v[204:205], v[204:205], 0, s[62:63]
	v_pk_mul_f32 v[82:83], v[82:83], v[82:83]
	v_pk_mul_f32 v[84:85], v[84:85], v[84:85]
	v_pk_mul_f32 v[86:87], v[86:87], v[86:87]
	v_pk_mul_f32 v[88:89], v[88:89], v[88:89]
	v_pk_mul_f32 v[90:91], v[90:91], v[90:91]
	v_pk_mul_f32 v[92:93], v[92:93], v[92:93]
	v_pk_mul_f32 v[94:95], v[94:95], v[94:95]
	v_pk_mul_f32 v[96:97], v[96:97], v[96:97]
	v_lshl_add_u64 v[204:205], v[204:205], 0, v[214:215]
	v_cvt_pk_bf16_f32 v94, v94, v95
	v_cvt_pk_bf16_f32 v95, v96, v97
	v_cvt_pk_bf16_f32 v96, v90, v91
	v_cvt_pk_bf16_f32 v97, v92, v93
	v_lshl_add_u64 v[206:207], v[204:205], 0, s[14:15]
	ds_bpermute_b32 v94, v211, v94
	ds_bpermute_b32 v95, v211, v95
	ds_bpermute_b32 v96, v211, v96
	ds_bpermute_b32 v97, v211, v97
	v_cvt_pk_bf16_f32 v86, v86, v87
	v_cvt_pk_bf16_f32 v87, v88, v89
	v_cvt_pk_bf16_f32 v88, v82, v83
	v_cvt_pk_bf16_f32 v89, v84, v85
	ds_bpermute_b32 v86, v211, v86
	ds_bpermute_b32 v87, v211, v87
	ds_bpermute_b32 v88, v211, v88
	ds_bpermute_b32 v89, v211, v89
	s_waitcnt lgkmcnt(8)
	global_store_dwordx4 v[216:217], v[110:113], off
	global_store_dwordx4 v[218:219], v[102:105], off
	v_pk_mul_f32 v[66:67], v[66:67], v[246:247] op_sel:[0,1]
	v_pk_mul_f32 v[68:69], v[68:69], v[246:247] op_sel:[0,1]
	v_pk_mul_f32 v[70:71], v[70:71], v[246:247] op_sel:[0,1]
	v_pk_mul_f32 v[72:73], v[72:73], v[246:247] op_sel:[0,1]
	v_pk_mul_f32 v[74:75], v[74:75], v[246:247] op_sel:[0,1]
	v_pk_mul_f32 v[76:77], v[76:77], v[246:247] op_sel:[0,1]
	v_pk_mul_f32 v[78:79], v[78:79], v[246:247] op_sel:[0,1]
	v_pk_mul_f32 v[80:81], v[80:81], v[246:247] op_sel:[0,1]
	v_lshl_add_u64 v[216:217], s[10:11], 0, v[150:151]
	v_max_f32_e32 v66, 0, v66
	v_max_f32_e32 v67, 0, v67
	v_max_f32_e32 v68, 0, v68
	v_max_f32_e32 v69, 0, v69
	v_max_f32_e32 v70, 0, v70
	v_max_f32_e32 v71, 0, v71
	v_max_f32_e32 v72, 0, v72
	v_max_f32_e32 v73, 0, v73
	v_max_f32_e32 v74, 0, v74
	v_max_f32_e32 v75, 0, v75
	v_max_f32_e32 v76, 0, v76
	v_max_f32_e32 v77, 0, v77
	v_max_f32_e32 v78, 0, v78
	v_max_f32_e32 v79, 0, v79
	v_max_f32_e32 v80, 0, v80
	v_max_f32_e32 v81, 0, v81
	v_lshl_add_u64 v[216:217], v[216:217], 0, s[62:63]
	v_pk_mul_f32 v[66:67], v[66:67], v[66:67]
	v_pk_mul_f32 v[68:69], v[68:69], v[68:69]
	v_pk_mul_f32 v[70:71], v[70:71], v[70:71]
	v_pk_mul_f32 v[72:73], v[72:73], v[72:73]
	v_pk_mul_f32 v[74:75], v[74:75], v[74:75]
	v_pk_mul_f32 v[76:77], v[76:77], v[76:77]
	v_pk_mul_f32 v[78:79], v[78:79], v[78:79]
	v_pk_mul_f32 v[80:81], v[80:81], v[80:81]
	v_lshl_add_u64 v[216:217], v[216:217], 0, v[214:215]
	v_cvt_pk_bf16_f32 v78, v78, v79
	v_cvt_pk_bf16_f32 v79, v80, v81
	v_cvt_pk_bf16_f32 v80, v74, v75
	v_cvt_pk_bf16_f32 v81, v76, v77
	v_lshl_add_u64 v[218:219], v[216:217], 0, s[14:15]
	ds_bpermute_b32 v78, v211, v78
	ds_bpermute_b32 v79, v211, v79
	ds_bpermute_b32 v80, v211, v80
	ds_bpermute_b32 v81, v211, v81
	v_cvt_pk_bf16_f32 v70, v70, v71
	v_cvt_pk_bf16_f32 v71, v72, v73
	v_cvt_pk_bf16_f32 v72, v66, v67
	v_cvt_pk_bf16_f32 v73, v68, v69
	ds_bpermute_b32 v70, v211, v70
	ds_bpermute_b32 v71, v211, v71
	ds_bpermute_b32 v72, v211, v72
	ds_bpermute_b32 v73, v211, v73
	s_waitcnt lgkmcnt(8)
	global_store_dwordx4 v[204:205], v[94:97], off
	global_store_dwordx4 v[206:207], v[86:89], off
	v_pk_mul_f32 v[50:51], v[50:51], v[248:249] op_sel_hi:[1,0]
	v_pk_mul_f32 v[52:53], v[52:53], v[248:249] op_sel_hi:[1,0]
	v_pk_mul_f32 v[54:55], v[54:55], v[248:249] op_sel_hi:[1,0]
	v_pk_mul_f32 v[56:57], v[56:57], v[248:249] op_sel_hi:[1,0]
	v_pk_mul_f32 v[58:59], v[58:59], v[248:249] op_sel_hi:[1,0]
	v_pk_mul_f32 v[60:61], v[60:61], v[248:249] op_sel_hi:[1,0]
	v_pk_mul_f32 v[62:63], v[62:63], v[248:249] op_sel_hi:[1,0]
	v_pk_mul_f32 v[64:65], v[64:65], v[248:249] op_sel_hi:[1,0]
	v_lshl_add_u64 v[204:205], s[10:11], 0, v[152:153]
	v_max_f32_e32 v50, 0, v50
	v_max_f32_e32 v51, 0, v51
	v_max_f32_e32 v52, 0, v52
	v_max_f32_e32 v53, 0, v53
	v_max_f32_e32 v54, 0, v54
	v_max_f32_e32 v55, 0, v55
	v_max_f32_e32 v56, 0, v56
	v_max_f32_e32 v57, 0, v57
	v_max_f32_e32 v58, 0, v58
	v_max_f32_e32 v59, 0, v59
	v_max_f32_e32 v60, 0, v60
	v_max_f32_e32 v61, 0, v61
	v_max_f32_e32 v62, 0, v62
	v_max_f32_e32 v63, 0, v63
	v_max_f32_e32 v64, 0, v64
	v_max_f32_e32 v65, 0, v65
	v_lshl_add_u64 v[204:205], v[204:205], 0, s[62:63]
	v_pk_mul_f32 v[50:51], v[50:51], v[50:51]
	v_pk_mul_f32 v[52:53], v[52:53], v[52:53]
	v_pk_mul_f32 v[54:55], v[54:55], v[54:55]
	v_pk_mul_f32 v[56:57], v[56:57], v[56:57]
	v_pk_mul_f32 v[58:59], v[58:59], v[58:59]
	v_pk_mul_f32 v[60:61], v[60:61], v[60:61]
	v_pk_mul_f32 v[62:63], v[62:63], v[62:63]
	v_pk_mul_f32 v[64:65], v[64:65], v[64:65]
	v_lshl_add_u64 v[204:205], v[204:205], 0, v[214:215]
	v_cvt_pk_bf16_f32 v62, v62, v63
	v_cvt_pk_bf16_f32 v63, v64, v65
	v_cvt_pk_bf16_f32 v64, v58, v59
	v_cvt_pk_bf16_f32 v65, v60, v61
	v_lshl_add_u64 v[206:207], v[204:205], 0, s[14:15]
	ds_bpermute_b32 v62, v211, v62
	ds_bpermute_b32 v63, v211, v63
	ds_bpermute_b32 v64, v211, v64
	ds_bpermute_b32 v65, v211, v65
	v_cvt_pk_bf16_f32 v54, v54, v55
	v_cvt_pk_bf16_f32 v55, v56, v57
	v_cvt_pk_bf16_f32 v56, v50, v51
	v_cvt_pk_bf16_f32 v57, v52, v53
	ds_bpermute_b32 v54, v211, v54
	ds_bpermute_b32 v55, v211, v55
	ds_bpermute_b32 v56, v211, v56
	ds_bpermute_b32 v57, v211, v57
	s_waitcnt lgkmcnt(8)
; __device__ __forceinline__ unsigned pk2(float lo, float hi) { f32x2 v = {lo, hi}; bf16x2_t b = __builtin_convertvector(v, bf16x2_t); return __builtin_bit_cast(unsigned, b); }
;     __device__ __forceinline__ void operator()(const f32x4 (&acc)[2][2][4][2], const Unit& u, int wr, int wc, int fr, int fq) const {
; #pragma unroll
;         for (int ai = 0; ai < 2; ++ai)
; #pragma unroll
;             for (int m = 0; m < 4; ++m) {
;                 const size_t row = (size_t)u.pm * 256 + 128 * wr + 64 * ai + 16 * m + fr;
;                 const f32x4* sp = (const f32x4*)(ssq + row * 16);
;                 const f32x4 t = (sp[0] + sp[1]) + (sp[2] + sp[3]);
;                 const float r = __builtin_amdgcn_rsqf(((t[0] + t[1]) + (t[2] + t[3])) * (1.0f / DM) + EPS);
;                 const size_t off = (((size_t)u.pm * 64 + 4 * u.pn + (wc >> 1)) * 256 + (128 * wr + 64 * ai + 16 * m + fr)) * 64 + 32 * (wc & 1) + 8 * fq;
; #pragma unroll
;                 for (int bj = 0; bj < 2; ++bj) {
;                     f32x4 v0 = acc[ai][bj][m][0] * r, v1 = acc[ai][bj][m][1] * r;
; #pragma unroll
;                     for (int j = 0; j < 4; ++j) { v0[j] = fmaxf(v0[j], 0.f); v1[j] = fmaxf(v1[j], 0.f); }
;                     v0 = v0 * v0; v1 = v1 * v1;
;                     u32x4 w; w.x = pk2(v0[0], v0[1]); w.y = pk2(v0[2], v0[3]); w.z = pk2(v1[0], v1[1]); w.w = pk2(v1[2], v1[3]);
;                     *(u32x4*)(H + off + (size_t)bj * (2 * 256 * 64)) = w;
;                 }
	global_store_dwordx4 v[216:217], v[78:81], off
	global_store_dwordx4 v[218:219], v[70:73], off
	v_pk_mul_f32 v[34:35], v[34:35], v[248:249] op_sel:[0,1]
	v_pk_mul_f32 v[36:37], v[36:37], v[248:249] op_sel:[0,1]
	v_pk_mul_f32 v[38:39], v[38:39], v[248:249] op_sel:[0,1]
	v_pk_mul_f32 v[40:41], v[40:41], v[248:249] op_sel:[0,1]
	v_pk_mul_f32 v[42:43], v[42:43], v[248:249] op_sel:[0,1]
	v_pk_mul_f32 v[44:45], v[44:45], v[248:249] op_sel:[0,1]
	v_pk_mul_f32 v[46:47], v[46:47], v[248:249] op_sel:[0,1]
	v_pk_mul_f32 v[48:49], v[48:49], v[248:249] op_sel:[0,1]
	v_lshl_add_u64 v[216:217], s[10:11], 0, v[154:155]
	v_max_f32_e32 v34, 0, v34
	v_max_f32_e32 v35, 0, v35
	v_max_f32_e32 v36, 0, v36
	v_max_f32_e32 v37, 0, v37
	v_max_f32_e32 v38, 0, v38
	v_max_f32_e32 v39, 0, v39
	v_max_f32_e32 v40, 0, v40
	v_max_f32_e32 v41, 0, v41
	v_max_f32_e32 v42, 0, v42
	v_max_f32_e32 v43, 0, v43
	v_max_f32_e32 v44, 0, v44
	v_max_f32_e32 v45, 0, v45
	v_max_f32_e32 v46, 0, v46
	v_max_f32_e32 v47, 0, v47
	v_max_f32_e32 v48, 0, v48
	v_max_f32_e32 v49, 0, v49
	v_lshl_add_u64 v[216:217], v[216:217], 0, s[62:63]
	v_pk_mul_f32 v[34:35], v[34:35], v[34:35]
	v_pk_mul_f32 v[36:37], v[36:37], v[36:37]
	v_pk_mul_f32 v[38:39], v[38:39], v[38:39]
	v_pk_mul_f32 v[40:41], v[40:41], v[40:41]
	v_pk_mul_f32 v[42:43], v[42:43], v[42:43]
	v_pk_mul_f32 v[44:45], v[44:45], v[44:45]
	v_pk_mul_f32 v[46:47], v[46:47], v[46:47]
	v_pk_mul_f32 v[48:49], v[48:49], v[48:49]
	v_lshl_add_u64 v[216:217], v[216:217], 0, v[214:215]
	v_cvt_pk_bf16_f32 v46, v46, v47
	v_cvt_pk_bf16_f32 v47, v48, v49
	v_cvt_pk_bf16_f32 v48, v42, v43
	v_cvt_pk_bf16_f32 v49, v44, v45
	v_lshl_add_u64 v[218:219], v[216:217], 0, s[14:15]
	ds_bpermute_b32 v46, v211, v46
	ds_bpermute_b32 v47, v211, v47
	ds_bpermute_b32 v48, v211, v48
	ds_bpermute_b32 v49, v211, v49
	v_cvt_pk_bf16_f32 v38, v38, v39
	v_cvt_pk_bf16_f32 v39, v40, v41
	v_cvt_pk_bf16_f32 v40, v34, v35
	v_cvt_pk_bf16_f32 v41, v36, v37
	ds_bpermute_b32 v38, v211, v38
	ds_bpermute_b32 v39, v211, v39
	ds_bpermute_b32 v40, v211, v40
	ds_bpermute_b32 v41, v211, v41
	s_waitcnt lgkmcnt(8)
	global_store_dwordx4 v[204:205], v[62:65], off
	global_store_dwordx4 v[206:207], v[54:57], off
	v_pk_mul_f32 v[18:19], v[18:19], v[250:251] op_sel_hi:[1,0]
	v_pk_mul_f32 v[20:21], v[20:21], v[250:251] op_sel_hi:[1,0]
	v_pk_mul_f32 v[22:23], v[22:23], v[250:251] op_sel_hi:[1,0]
	v_pk_mul_f32 v[24:25], v[24:25], v[250:251] op_sel_hi:[1,0]
	v_pk_mul_f32 v[26:27], v[26:27], v[250:251] op_sel_hi:[1,0]
	v_pk_mul_f32 v[28:29], v[28:29], v[250:251] op_sel_hi:[1,0]
	v_pk_mul_f32 v[30:31], v[30:31], v[250:251] op_sel_hi:[1,0]
	v_pk_mul_f32 v[32:33], v[32:33], v[250:251] op_sel_hi:[1,0]
	v_lshl_add_u64 v[204:205], s[10:11], 0, v[156:157]
	v_max_f32_e32 v18, 0, v18
	v_max_f32_e32 v19, 0, v19
	v_max_f32_e32 v20, 0, v20
	v_max_f32_e32 v21, 0, v21
	v_max_f32_e32 v22, 0, v22
	v_max_f32_e32 v23, 0, v23
	v_max_f32_e32 v24, 0, v24
	v_max_f32_e32 v25, 0, v25
	v_max_f32_e32 v26, 0, v26
	v_max_f32_e32 v27, 0, v27
	v_max_f32_e32 v28, 0, v28
	v_max_f32_e32 v29, 0, v29
	v_max_f32_e32 v30, 0, v30
	v_max_f32_e32 v31, 0, v31
	v_max_f32_e32 v32, 0, v32
	v_max_f32_e32 v33, 0, v33
	v_lshl_add_u64 v[204:205], v[204:205], 0, s[62:63]
	v_pk_mul_f32 v[18:19], v[18:19], v[18:19]
	v_pk_mul_f32 v[20:21], v[20:21], v[20:21]
	v_pk_mul_f32 v[22:23], v[22:23], v[22:23]
	v_pk_mul_f32 v[24:25], v[24:25], v[24:25]
	v_pk_mul_f32 v[26:27], v[26:27], v[26:27]
	v_pk_mul_f32 v[28:29], v[28:29], v[28:29]
	v_pk_mul_f32 v[30:31], v[30:31], v[30:31]
	v_pk_mul_f32 v[32:33], v[32:33], v[32:33]
	v_lshl_add_u64 v[204:205], v[204:205], 0, v[214:215]
	v_cvt_pk_bf16_f32 v30, v30, v31
	v_cvt_pk_bf16_f32 v31, v32, v33
	v_cvt_pk_bf16_f32 v32, v26, v27
	v_cvt_pk_bf16_f32 v33, v28, v29
	v_lshl_add_u64 v[206:207], v[204:205], 0, s[14:15]
	ds_bpermute_b32 v30, v211, v30
	ds_bpermute_b32 v31, v211, v31
	ds_bpermute_b32 v32, v211, v32
	ds_bpermute_b32 v33, v211, v33
	v_cvt_pk_bf16_f32 v22, v22, v23
	v_cvt_pk_bf16_f32 v23, v24, v25
	v_cvt_pk_bf16_f32 v24, v18, v19
	v_cvt_pk_bf16_f32 v25, v20, v21
	ds_bpermute_b32 v22, v211, v22
	ds_bpermute_b32 v23, v211, v23
	ds_bpermute_b32 v24, v211, v24
	ds_bpermute_b32 v25, v211, v25
	s_waitcnt lgkmcnt(8)
	global_store_dwordx4 v[216:217], v[46:49], off
	global_store_dwordx4 v[218:219], v[38:41], off
	v_pk_mul_f32 v[2:3], v[2:3], v[250:251] op_sel:[0,1]
	v_pk_mul_f32 v[4:5], v[4:5], v[250:251] op_sel:[0,1]
	v_pk_mul_f32 v[6:7], v[6:7], v[250:251] op_sel:[0,1]
	v_pk_mul_f32 v[8:9], v[8:9], v[250:251] op_sel:[0,1]
	v_pk_mul_f32 v[10:11], v[10:11], v[250:251] op_sel:[0,1]
	v_pk_mul_f32 v[12:13], v[12:13], v[250:251] op_sel:[0,1]
	v_pk_mul_f32 v[14:15], v[14:15], v[250:251] op_sel:[0,1]
	v_pk_mul_f32 v[16:17], v[16:17], v[250:251] op_sel:[0,1]
	v_lshl_add_u64 v[216:217], s[10:11], 0, v[158:159]
	v_max_f32_e32 v2, 0, v2
	v_max_f32_e32 v3, 0, v3
	v_max_f32_e32 v4, 0, v4
	v_max_f32_e32 v5, 0, v5
	v_max_f32_e32 v6, 0, v6
	v_max_f32_e32 v7, 0, v7
	v_max_f32_e32 v8, 0, v8
	v_max_f32_e32 v9, 0, v9
	v_max_f32_e32 v10, 0, v10
	v_max_f32_e32 v11, 0, v11
	v_max_f32_e32 v12, 0, v12
	v_max_f32_e32 v13, 0, v13
	v_max_f32_e32 v14, 0, v14
	v_max_f32_e32 v15, 0, v15
	v_max_f32_e32 v16, 0, v16
	v_max_f32_e32 v17, 0, v17
	v_lshl_add_u64 v[216:217], v[216:217], 0, s[62:63]
	v_pk_mul_f32 v[2:3], v[2:3], v[2:3]
	v_pk_mul_f32 v[4:5], v[4:5], v[4:5]
	v_pk_mul_f32 v[6:7], v[6:7], v[6:7]
	v_pk_mul_f32 v[8:9], v[8:9], v[8:9]
	v_pk_mul_f32 v[10:11], v[10:11], v[10:11]
	v_pk_mul_f32 v[12:13], v[12:13], v[12:13]
	v_pk_mul_f32 v[14:15], v[14:15], v[14:15]
	v_pk_mul_f32 v[16:17], v[16:17], v[16:17]
	v_lshl_add_u64 v[216:217], v[216:217], 0, v[214:215]
	v_cvt_pk_bf16_f32 v14, v14, v15
	v_cvt_pk_bf16_f32 v15, v16, v17
	v_cvt_pk_bf16_f32 v16, v10, v11
	v_cvt_pk_bf16_f32 v17, v12, v13
	v_lshl_add_u64 v[218:219], v[216:217], 0, s[14:15]
	ds_bpermute_b32 v14, v211, v14
	ds_bpermute_b32 v15, v211, v15
	ds_bpermute_b32 v16, v211, v16
	ds_bpermute_b32 v17, v211, v17
	v_cvt_pk_bf16_f32 v6, v6, v7
	v_cvt_pk_bf16_f32 v7, v8, v9
	v_cvt_pk_bf16_f32 v8, v2, v3
	v_cvt_pk_bf16_f32 v9, v4, v5
	ds_bpermute_b32 v6, v211, v6
	ds_bpermute_b32 v7, v211, v7
	ds_bpermute_b32 v8, v211, v8
	ds_bpermute_b32 v9, v211, v9
	s_waitcnt lgkmcnt(8)
	global_store_dwordx4 v[204:205], v[30:33], off
	global_store_dwordx4 v[206:207], v[22:25], off
	s_waitcnt lgkmcnt(0)
	global_store_dwordx4 v[216:217], v[14:17], off
	global_store_dwordx4 v[218:219], v[6:9], off
	s_mov_b64 s[6:7], -1
	s_andn2_b64 vcc, exec, s[36:37]
	s_cbranch_vccnz .LBB0_704
	s_andn2_b64 vcc, exec, s[96:97]
	s_cbranch_vccnz .LBB0_703
	s_barrier
	s_branch .LBB0_703
